# combined: atomics-free importance + balanced attention item order
# speedup vs baseline: 1.0290x; 1.0099x over previous
.LBB0_1929:
	s_or_b64 exec, exec, s[22:23]
	ds_write_b32 v175, v105 offset:8448
	ds_write_b32 v175, v105 offset:9472
	ds_write_b32 v175, v105 offset:10496
	ds_write_b32 v175, v105 offset:11520
	ds_write_b32 v175, v105 offset:12544
	ds_write_b32 v175, v105 offset:13568
	ds_write_b32 v175, v105 offset:14592
	ds_write_b32 v175, v105 offset:15616
	ds_write_b32 v175, v105 offset:16640
	s_lshl_b32 s20, s99, 1
	s_and_b32 s70, s20, -16
	s_sub_i32 s67, 0x1ff0, s70
	v_add_u32_e32 v132, s67, v103
	s_lshl_b32 s20, s99, 12
	s_and_b32 s54, s20, 0x6000
	s_mov_b32 s55, s39
	v_ashrrev_i32_e32 v133, 31, v132
	s_lshl_b32 s20, s99, 3
	v_lshl_add_u64 v[2:3], v[132:133], 0, s[54:55]
	s_and_b32 s55, s20, 8
	v_lshlrev_b64 v[4:5], 11, v[2:3]
	v_or_b32_e32 v6, s55, v102
	v_lshl_add_u64 v[4:5], s[42:43], 0, v[4:5]
	v_lshlrev_b32_e32 v104, 7, v6
	v_mad_u64_u32 v[6:7], s[20:21], v2, s49, v[124:125]
	v_lshl_add_u64 v[4:5], v[4:5], 0, v[104:105]
	v_mad_i32_i24 v7, v3, s49, v7
	s_lshl_b32 s20, s55, 2
	s_mov_b32 s21, s39
	v_lshl_add_u64 v[4:5], v[4:5], 0, v[122:123]
	v_lshl_add_u64 v[2:3], v[6:7], 0, s[20:21]
	global_load_dwordx4 v[66:69], v[4:5], off offset:32
	global_load_dwordx4 v[70:73], v[4:5], off offset:64
	global_load_dwordx4 v[74:77], v[4:5], off offset:96
	v_lshl_add_u64 v[130:131], v[2:3], 0, v[126:127]
	global_load_dwordx4 v[78:81], v[4:5], off
	global_load_dword v133, v[130:131], off
	global_load_dword v104, v[130:131], off offset:128
	s_and_b32 s20, s99, 7
	s_lshl_b32 s38, s20, 16
	s_lshr_b32 s20, s30, 4
	s_add_i32 s20, s20, 63
	s_lshr_b32 s20, s20, 6
	s_sub_i32 s28, 0, s20
	s_lshr_b32 s20, s67, 4
	s_and_b32 s71, s99, 7
	s_add_i32 s20, s20, 63
	s_lshr_b32 s29, s20, 6
	s_lshl_b32 s30, s71, 16
	s_add_u32 s22, s26, s30
	s_addc_u32 s23, s27, 0
	s_cmpk_lg_i32 s70, 0x1ff0
	s_cselect_b64 s[24:25], -1, 0
	s_cmpk_eq_i32 s70, 0x1ff0
	v_mov_b32_e32 v54, 0
	s_cbranch_scc1 .LBB0_1942
	v_mov_b32_e32 v129, v105
	v_lshl_add_u64 v[2:3], s[22:23], 0, v[128:129]
	v_lshl_add_u64 v[4:5], v[2:3], 0, v[106:107]
	v_lshl_add_u64 v[6:7], v[2:3], 0, v[108:109]
	global_load_dwordx4 v[34:37], v[4:5], off
	global_load_dwordx4 v[38:41], v[6:7], off
	s_cmp_eq_u32 s29, 1
	s_waitcnt vmcnt(1)
	ds_write_b128 v153, v[34:37]
	s_waitcnt vmcnt(0)
	ds_write_b128 v155, v[38:41]
	s_cbranch_scc1 .LBB0_1932
	v_lshl_add_u64 v[2:3], v[2:3], 0, s[40:41]
	v_lshl_add_u64 v[4:5], v[2:3], 0, v[106:107]
	v_lshl_add_u64 v[2:3], v[2:3], 0, v[108:109]
	global_load_dwordx4 v[34:37], v[4:5], off
	global_load_dwordx4 v[38:41], v[2:3], off
